# NA tile loop: prefetch depth 2 (two staging register sets alternating by tile parity) on top of lean NA tiles
# baseline (speedup 1.0000x reference)
.Lna_fake:
	s_mov_b32 s15, 0
	s_branch .LBB0_719

.LBB0_717:
	s_andn2_b64 vcc, exec, s[4:5]
	s_cbranch_vccnz .LBB0_799
	v_and_b32_e32 v0, 31, v4
	v_and_or_b32 v2, s7, 32, v0
	v_sub_u32_e64 v3, v2, 8 clamp
	v_min_u32_e32 v3, 48, v3
	v_mul_u32_u24_e32 v4, 0x48, v0
	v_mul_u32_u24_e32 v98, 0x90, v0
	v_or_b32_e32 v0, 32, v97
	v_lshlrev_b32_e32 v1, 3, v5
	v_sub_u32_e32 v0, v0, v3
	v_add_lshl_u32 v99, v1, v4, 1
	v_sub_u32_e32 v1, v97, v3
	v_cmp_gt_u32_e64 s[44:45], 16, v0
	v_or_b32_e32 v0, 1, v97
	v_cmp_gt_u32_e64 s[42:43], 16, v1
	v_or_b32_e32 v1, 33, v97
	v_sub_u32_e32 v0, v0, v3
	v_cmp_gt_u32_e64 s[46:47], 16, v0
	v_sub_u32_e32 v0, v1, v3
	v_cmp_gt_u32_e64 s[48:49], 16, v0
	v_or_b32_e32 v0, 2, v97
	v_or_b32_e32 v1, 34, v97
	v_sub_u32_e32 v0, v0, v3
	v_cmp_gt_u32_e64 s[50:51], 16, v0
	v_sub_u32_e32 v0, v1, v3
	v_cmp_gt_u32_e64 s[52:53], 16, v0
	v_or_b32_e32 v0, 3, v97
	v_or_b32_e32 v1, 35, v97
	v_sub_u32_e32 v0, v0, v3
	v_cmp_gt_u32_e64 s[54:55], 16, v0
	v_sub_u32_e32 v0, v1, v3
	s_mov_b64 s[24:25], s[56:57]
	v_cmp_gt_u32_e64 s[56:57], 16, v0
	v_or_b32_e32 v0, 8, v97
	v_or_b32_e32 v1, 40, v97
	v_sub_u32_e32 v0, v0, v3
	v_cmp_gt_u32_e64 s[58:59], 16, v0
	v_sub_u32_e32 v0, v1, v3
	v_cmp_gt_u32_e64 s[60:61], 16, v0
	v_or_b32_e32 v0, 9, v97
	v_or_b32_e32 v1, 41, v97
	v_sub_u32_e32 v0, v0, v3
	v_cmp_gt_u32_e64 s[62:63], 16, v0
	v_sub_u32_e32 v0, v1, v3
	v_cmp_gt_u32_e64 s[64:65], 16, v0
	v_or_b32_e32 v0, 10, v97
	v_or_b32_e32 v1, 42, v97
	v_sub_u32_e32 v0, v0, v3
	v_cmp_gt_u32_e64 s[66:67], 16, v0
	v_sub_u32_e32 v0, v1, v3
	v_cmp_gt_u32_e64 s[68:69], 16, v0
	v_or_b32_e32 v0, 11, v97
	v_or_b32_e32 v1, 43, v97
	v_sub_u32_e32 v0, v0, v3
	v_cmp_gt_u32_e64 s[70:71], 16, v0
	v_sub_u32_e32 v0, v1, v3
	v_cmp_gt_u32_e64 s[72:73], 16, v0
	v_or_b32_e32 v0, 16, v97
	v_or_b32_e32 v1, 48, v97
	v_sub_u32_e32 v0, v0, v3
	v_cmp_gt_u32_e64 s[74:75], 16, v0
	v_sub_u32_e32 v0, v1, v3
	v_cmp_gt_u32_e64 s[76:77], 16, v0
	v_or_b32_e32 v0, 17, v97
	v_or_b32_e32 v1, 49, v97
	v_sub_u32_e32 v0, v0, v3
	v_cmp_gt_u32_e64 s[78:79], 16, v0
	v_sub_u32_e32 v0, v1, v3
	v_cmp_gt_u32_e64 s[80:81], 16, v0
	v_or_b32_e32 v0, 18, v97
	v_or_b32_e32 v1, 50, v97
	v_sub_u32_e32 v0, v0, v3
	v_cmp_gt_u32_e64 s[82:83], 16, v0
	v_sub_u32_e32 v0, v1, v3
	v_cmp_gt_u32_e64 s[84:85], 16, v0
	v_or_b32_e32 v0, 19, v97
	v_or_b32_e32 v1, 51, v97
	v_sub_u32_e32 v0, v0, v3
	v_cmp_gt_u32_e64 s[86:87], 16, v0
	v_sub_u32_e32 v0, v1, v3
	v_cmp_gt_u32_e64 s[88:89], 16, v0
	v_or_b32_e32 v0, 24, v97
	v_or_b32_e32 v1, 56, v97
	v_sub_u32_e32 v0, v0, v3
	v_cmp_gt_u32_e64 s[90:91], 16, v0
	v_sub_u32_e32 v0, v1, v3
	v_cmp_gt_u32_e64 s[92:93], 16, v0
	v_or_b32_e32 v0, 25, v97
	s_ashr_i32 s19, s6, 7
	v_or_b32_e32 v1, 57, v97
	v_sub_u32_e32 v0, v0, v3
	s_add_i32 s1, s19, s1
	v_cmp_gt_u32_e64 s[94:95], 16, v0
	v_sub_u32_e32 v0, v1, v3
	s_max_i32 s1, s1, 4
	v_cmp_gt_u32_e64 s[96:97], 16, v0
	v_or_b32_e32 v0, 26, v97
	s_add_i32 s1, s1, -4
	v_or_b32_e32 v1, 58, v97
	v_sub_u32_e32 v0, v0, v3
	s_min_u32 s12, s1, 56
	v_cmp_gt_u32_e64 s[4:5], 16, v0
	v_sub_u32_e32 v0, v1, v3
	s_mul_i32 s1, s14, 31
	s_mul_i32 s19, s19, 31
	v_cmp_gt_u32_e64 s[6:7], 16, v0
	v_or_b32_e32 v0, 27, v97
	s_sub_i32 s1, s1, s19
	s_mulk_i32 s0, 0x7c
	v_or_b32_e32 v1, 59, v97
	v_sub_u32_e32 v0, v0, v3
	s_sub_i32 s0, s1, s0
	v_cmp_gt_u32_e64 s[8:9], 16, v0
	v_sub_u32_e32 v0, v1, v3
	s_add_i32 s21, s0, 0x5d
	s_sub_i32 s0, s14, s15
	v_cmp_gt_u32_e64 s[10:11], 16, v0
	v_lshlrev_b32_e32 v0, 2, v2
	s_lshl_b32 s0, s0, 6
	s_add_i32 s13, s12, 8
	s_add_i32 s38, s39, 15
	s_add_i32 s39, s39, 16
	v_sub_u32_e32 v101, 0, v0
	s_add_i32 s1, s0, 0xfffffd40
	v_lshl_add_u32 v0, s14, 6, v92
	s_lshl_b32 s0, s15, 6
	v_subrev_u32_e32 v0, s0, v0
	s_add_u32 s0, s24, s18
	v_add_u32_e32 v0, 0xfffffd40, v0
	s_addc_u32 s15, s25, 0
	v_ashrrev_i32_e32 v1, 31, v0
	s_add_u32 s14, s0, s16
	v_lshlrev_b64 v[0:1], 11, v[0:1]
	s_addc_u32 s15, s15, s17
	v_mov_b32_e32 v14, v131
	v_mov_b32_e32 v15, v131
	v_lshl_add_u64 v[94:95], s[14:15], 0, v[0:1]
	v_mov_b32_e32 v0, v131
	v_mov_b32_e32 v1, v131
	v_mov_b32_e32 v2, v131
	v_mov_b32_e32 v3, v131
	v_mov_b32_e32 v4, v131
	v_mov_b32_e32 v5, v131
	v_mov_b32_e32 v6, v131
	v_mov_b32_e32 v7, v131
	v_mov_b32_e32 v8, v131
	v_mov_b32_e32 v9, v131
	v_mov_b32_e32 v10, v131
	v_mov_b32_e32 v11, v131
	v_mov_b32_e32 v12, v131
	v_mov_b32_e32 v13, v131
	v_lshlrev_b32_e32 v130, 1, v16
	v_mov_b64_e32 v[30:31], v[14:15]
	v_add_u32_e32 v100, 0x1200, v99
	s_mov_b32 s15, -1
	s_add_i32 s1, s1, 64
	s_mov_b64 s[16:17], 0x20000
	s_nop 0
	v_lshl_add_u64 v[94:95], v[94:95], 0, s[16:17]
	s_mov_b32 s32, 0
	v_mov_b32_e32 v102, 0
	v_mov_b32_e32 v96, 0xff800000
	v_mov_b64_e32 v[28:29], v[12:13]
	v_mov_b64_e32 v[26:27], v[10:11]
	v_mov_b64_e32 v[24:25], v[8:9]
	v_mov_b64_e32 v[22:23], v[6:7]
	v_mov_b64_e32 v[20:21], v[4:5]
	v_mov_b64_e32 v[18:19], v[2:3]
	v_mov_b64_e32 v[16:17], v[0:1]
.LBB0_719:
	s_add_i32 s14, s15, 1
	s_cmp_lt_i32 s15, s38
	s_cselect_b64 s[16:17], -1, 0
	s_cmp_ge_i32 s14, s38
	s_cbranch_scc1 .LBB0_723
	s_mov_b64 s[18:19], 0x100
	s_add_i32 s0, s14, 1
	s_cmp_ge_i32 s0, s33
	s_mov_b64 vcc, s[36:37]
	s_mov_b32 s26, s1
	v_mov_b64_e32 v[32:33], v[94:95]
	s_cbranch_scc1 .LBB0_722
	s_lshl_b32 s26, s0, 6
	v_add_u32_e32 v34, s26, v92
	v_mov_b64_e32 v[32:33], s[40:41]
	s_movk_i32 s0, 0x1800
	v_mad_i64_i32 v[32:33], s[18:19], v34, s0, v[32:33]
	s_mov_b64 s[18:19], 0x800
	s_nop 0
	v_lshl_add_u64 v[32:33], v[32:33], 0, s[18:19]
	s_mov_b64 s[18:19], 0xa000
	s_mov_b64 vcc, s[28:29]
.LBB0_722:
	v_mad_i64_i32 v[34:35], s[18:19], s18, v92, 0
	v_lshl_add_u64 v[34:35], v[34:35], 1, vcc
	v_lshl_add_u64 v[34:35], s[26:27], 1, v[34:35]
	v_lshl_add_u64 v[32:33], v[32:33], 0, v[130:131]
	v_lshl_add_u64 v[34:35], v[34:35], 0, v[130:131]
	s_bitcmp1_b32 s15, 0
	s_cbranch_scc1 .Lna_ldB
	global_load_dwordx4 v[80:83], v[32:33], off
	global_load_dwordx4 v[84:87], v[34:35], off
	s_branch .LBB0_723
.Lna_ldB:
	global_load_dwordx4 v[150:153], v[32:33], off
	global_load_dwordx4 v[154:157], v[34:35], off
.LBB0_723:
	s_cmp_lt_i32 s15, 0
	s_cbranch_scc1 .Lna_fake
	s_cmp_lt_i32 s15, s33
	s_cselect_b64 s[18:19], -1, 0
	s_cmp_ge_i32 s15, s33
	s_cbranch_scc1 .LBB0_725
	s_add_i32 s0, s3, s15
	s_cmp_ge_u32 s0, s12
	s_cselect_b64 vcc, -1, 0
	s_cmp_lt_u32 s0, s13
	s_cselect_b64 s[24:25], -1, 0
	s_and_b64 vcc, vcc, s[24:25]
	s_mov_b32 s0, s21
	s_andn2_b64 vcc, exec, vcc
	s_and_b32 s15, s15, 1
	s_cbranch_vccz .LBB0_726
	s_branch .LBB0_795

.LBB0_795:
	s_andn2_b64 vcc, exec, s[16:17]
	s_cbranch_vccnz .LBB0_797
	s_xor_b32 s0, s15, 1
	s_mulk_i32 s0, 0x4800
	s_add_i32 s0, s0, 0
	v_add_u32_e32 v32, s0, v93
	v_add_u32_e32 v33, s0, v91
	v_add_u32_e32 v32, 0x2000, v32
	s_cmp_lt_i32 s14, s38
	s_cbranch_scc1 .Lna_w2
	s_waitcnt vmcnt(0)
	s_branch .Lna_w
.Lna_w2:
	s_waitcnt vmcnt(2)
.Lna_w:
	s_cmp_eq_u32 s15, 0
	s_cbranch_scc1 .Lna_wB
	ds_write_b128 v33, v[80:83]
	ds_write2_b64 v32, v[84:85], v[86:87] offset0:128 offset1:130
	s_branch .LBB0_797
.Lna_wB:
	ds_write_b128 v33, v[150:153]
	ds_write2_b64 v32, v[154:155], v[156:157] offset0:128 offset1:130
